# FFN1 hand epilogue with trans/VALU interleave across 3 row streams (list-scheduled)
# speedup vs baseline: 1.0013x; 1.0013x over previous
.LBB0_1498:
	v_mov_b32_e32 v142, v147
	v_mov_b32_e32 v153, v146
	s_lshl_b32 s0, s63, 8
	s_add_i32 s0, s0, s53
	v_add_u32_e32 v142, s0, v142
	v_ashrrev_i32_e32 v143, 31, v142
	v_lshl_add_u64 v[144:145], v[142:143], 2, s[18:19]
	global_load_dword v152, v[144:145], off
	global_load_dword v233, v[144:145], off offset:64
	global_load_dword v234, v[144:145], off offset:128
	global_load_dword v235, v[144:145], off offset:192
	global_load_dword v236, v[144:145], off offset:512
	global_load_dword v237, v[144:145], off offset:576
	global_load_dword v238, v[144:145], off offset:640
	global_load_dword v239, v[144:145], off offset:704
	s_lshl_b32 s0, s62, 7
	s_or_b32 s0, s0, s54
	v_lshl_add_u32 v156, v153, 3, s0
	v_ashrrev_i32_e32 v157, 31, v156
	v_mov_b64_e32 v[160:161], s[10:11]
	v_mad_i64_i32 v[154:155], s[0:1], v142, s59, v[160:161]
	v_lshlrev_b64 v[160:161], 1, v[156:157]
	v_lshl_add_u64 v[154:155], v[154:155], 0, v[160:161]
	v_mov_b32_e32 v158, 1.0
	v_mov_b32_e32 v159, 1.0
	s_waitcnt vmcnt(0)
	v_mul_f32_e32 v160, 0xbfb8aa3b, v152
	v_mul_f32_e32 v162, v152, v152
	v_pk_mul_f32 v[164:165], v[120:121], v[160:161] op_sel_hi:[1,0]
	v_pk_mul_f32 v[166:167], v[122:123], v[160:161] op_sel_hi:[1,0]
	v_pk_mul_f32 v[168:169], v[112:113], v[160:161] op_sel_hi:[1,0]
	v_pk_mul_f32 v[170:171], v[114:115], v[160:161] op_sel_hi:[1,0]
	v_exp_f32_e32 v164, v164
	v_mul_f32_e32 v182, 0xbfb8aa3b, v233
	v_exp_f32_e32 v165, v165
	v_mul_f32_e32 v184, v233, v233
	v_exp_f32_e32 v166, v166
	v_pk_mul_f32 v[186:187], v[104:105], v[182:183] op_sel_hi:[1,0]
	v_exp_f32_e32 v167, v167
	v_pk_mul_f32 v[188:189], v[106:107], v[182:183] op_sel_hi:[1,0]
	v_exp_f32_e32 v168, v168
	v_pk_mul_f32 v[190:191], v[96:97], v[182:183] op_sel_hi:[1,0]
	v_exp_f32_e32 v169, v169
	v_pk_mul_f32 v[192:193], v[98:99], v[182:183] op_sel_hi:[1,0]
	v_exp_f32_e32 v170, v170
	v_mul_f32_e32 v204, 0xbfb8aa3b, v234
	v_exp_f32_e32 v171, v171
	v_pk_mul_f32 v[172:173], v[120:121], v[124:125]
	v_exp_f32_e32 v186, v186
	v_pk_mul_f32 v[174:175], v[122:123], v[126:127]
	v_exp_f32_e32 v187, v187
	v_pk_mul_f32 v[176:177], v[112:113], v[116:117]
	v_exp_f32_e32 v188, v188
	v_pk_mul_f32 v[178:179], v[114:115], v[118:119]
	v_exp_f32_e32 v189, v189
	v_pk_add_f32 v[164:165], v[164:165], v[158:159]
	v_exp_f32_e32 v190, v190
	v_pk_add_f32 v[166:167], v[166:167], v[158:159]
	v_exp_f32_e32 v191, v191
	v_pk_add_f32 v[168:169], v[168:169], v[158:159]
	v_exp_f32_e32 v192, v192
	v_pk_add_f32 v[170:171], v[170:171], v[158:159]
	v_rcp_f32_e32 v164, v164
	v_mul_f32_e32 v206, v234, v234
	v_rcp_f32_e32 v165, v165
	v_pk_mul_f32 v[208:209], v[88:89], v[204:205] op_sel_hi:[1,0]
	v_rcp_f32_e32 v166, v166
	v_pk_mul_f32 v[210:211], v[90:91], v[204:205] op_sel_hi:[1,0]
	v_rcp_f32_e32 v167, v167
	v_pk_mul_f32 v[212:213], v[80:81], v[204:205] op_sel_hi:[1,0]
	v_rcp_f32_e32 v168, v168
	v_pk_mul_f32 v[214:215], v[82:83], v[204:205] op_sel_hi:[1,0]
	v_rcp_f32_e32 v169, v169
	v_rcp_f32_e32 v170, v170
	v_rcp_f32_e32 v171, v171
	v_pk_mul_f32 v[164:165], v[164:165], v[162:163] op_sel_hi:[1,0]
	v_exp_f32_e32 v193, v193
	v_pk_mul_f32 v[166:167], v[166:167], v[162:163] op_sel_hi:[1,0]
	v_exp_f32_e32 v208, v208
	v_pk_mul_f32 v[168:169], v[168:169], v[162:163] op_sel_hi:[1,0]
	v_exp_f32_e32 v209, v209
	v_pk_mul_f32 v[170:171], v[170:171], v[162:163] op_sel_hi:[1,0]
	v_exp_f32_e32 v210, v210
	v_pk_mul_f32 v[172:173], v[172:173], v[164:165]
	v_exp_f32_e32 v211, v211
	v_pk_mul_f32 v[174:175], v[174:175], v[166:167]
	v_exp_f32_e32 v212, v212
	v_pk_mul_f32 v[176:177], v[176:177], v[168:169]
	v_exp_f32_e32 v213, v213
	v_pk_mul_f32 v[178:179], v[178:179], v[170:171]
	v_exp_f32_e32 v214, v214
	v_cvt_pk_bf16_f32 v164, v172, v173
	v_exp_f32_e32 v215, v215
	v_cvt_pk_bf16_f32 v165, v174, v175
	v_cvt_pk_bf16_f32 v166, v176, v177
	v_cvt_pk_bf16_f32 v167, v178, v179
	global_store_dwordx4 v[154:155], v[164:167], off
	v_pk_mul_f32 v[194:195], v[104:105], v[108:109]
	v_pk_mul_f32 v[196:197], v[106:107], v[110:111]
	v_pk_mul_f32 v[198:199], v[96:97], v[100:101]
	v_pk_mul_f32 v[200:201], v[98:99], v[102:103]
	v_pk_add_f32 v[186:187], v[186:187], v[158:159]
	v_pk_add_f32 v[188:189], v[188:189], v[158:159]
	v_pk_add_f32 v[190:191], v[190:191], v[158:159]
	v_pk_add_f32 v[192:193], v[192:193], v[158:159]
	v_rcp_f32_e32 v186, v186
	v_pk_mul_f32 v[216:217], v[88:89], v[92:93]
	v_rcp_f32_e32 v187, v187
	v_pk_mul_f32 v[218:219], v[90:91], v[94:95]
	v_rcp_f32_e32 v188, v188
	v_pk_mul_f32 v[220:221], v[80:81], v[84:85]
	v_rcp_f32_e32 v189, v189
	v_pk_mul_f32 v[222:223], v[82:83], v[86:87]
	v_rcp_f32_e32 v190, v190
	v_pk_add_f32 v[208:209], v[208:209], v[158:159]
	v_rcp_f32_e32 v191, v191
	v_pk_add_f32 v[210:211], v[210:211], v[158:159]
	v_rcp_f32_e32 v192, v192
	v_pk_add_f32 v[212:213], v[212:213], v[158:159]
	v_rcp_f32_e32 v193, v193
	v_pk_mul_f32 v[186:187], v[186:187], v[184:185] op_sel_hi:[1,0]
	v_pk_mul_f32 v[188:189], v[188:189], v[184:185] op_sel_hi:[1,0]
	v_pk_mul_f32 v[190:191], v[190:191], v[184:185] op_sel_hi:[1,0]
	v_pk_mul_f32 v[192:193], v[192:193], v[184:185] op_sel_hi:[1,0]
	v_pk_mul_f32 v[194:195], v[194:195], v[186:187]
	v_pk_mul_f32 v[196:197], v[196:197], v[188:189]
	v_pk_mul_f32 v[198:199], v[198:199], v[190:191]
	v_pk_mul_f32 v[200:201], v[200:201], v[192:193]
	v_cvt_pk_bf16_f32 v186, v194, v195
	v_cvt_pk_bf16_f32 v187, v196, v197
	v_cvt_pk_bf16_f32 v188, v198, v199
	v_cvt_pk_bf16_f32 v189, v200, v201
	s_mov_b64 s[98:99], 0x2c000
	v_lshl_add_u64 v[202:203], v[154:155], 0, s[98:99]
	global_store_dwordx4 v[202:203], v[186:189], off
	v_pk_add_f32 v[214:215], v[214:215], v[158:159]
	v_rcp_f32_e32 v208, v208
	v_mul_f32_e32 v160, 0xbfb8aa3b, v235
	v_rcp_f32_e32 v209, v209
	v_mul_f32_e32 v162, v235, v235
	v_rcp_f32_e32 v210, v210
	v_pk_mul_f32 v[164:165], v[72:73], v[160:161] op_sel_hi:[1,0]
	v_rcp_f32_e32 v211, v211
	v_pk_mul_f32 v[166:167], v[74:75], v[160:161] op_sel_hi:[1,0]
	v_rcp_f32_e32 v212, v212
	v_pk_mul_f32 v[168:169], v[64:65], v[160:161] op_sel_hi:[1,0]
	v_rcp_f32_e32 v213, v213
	v_pk_mul_f32 v[170:171], v[66:67], v[160:161] op_sel_hi:[1,0]
	v_rcp_f32_e32 v214, v214
	v_mul_f32_e32 v182, 0xbfb8aa3b, v236
	v_rcp_f32_e32 v215, v215
	v_pk_mul_f32 v[208:209], v[208:209], v[206:207] op_sel_hi:[1,0]
	v_exp_f32_e32 v164, v164
	v_pk_mul_f32 v[210:211], v[210:211], v[206:207] op_sel_hi:[1,0]
	v_exp_f32_e32 v165, v165
	v_pk_mul_f32 v[212:213], v[212:213], v[206:207] op_sel_hi:[1,0]
	v_exp_f32_e32 v166, v166
	v_pk_mul_f32 v[214:215], v[214:215], v[206:207] op_sel_hi:[1,0]
	v_exp_f32_e32 v167, v167
	v_pk_mul_f32 v[216:217], v[216:217], v[208:209]
	v_exp_f32_e32 v168, v168
	v_pk_mul_f32 v[218:219], v[218:219], v[210:211]
	v_exp_f32_e32 v169, v169
	v_pk_mul_f32 v[220:221], v[220:221], v[212:213]
	v_exp_f32_e32 v170, v170
	v_pk_mul_f32 v[222:223], v[222:223], v[214:215]
	v_exp_f32_e32 v171, v171
	v_cvt_pk_bf16_f32 v208, v216, v217
	v_cvt_pk_bf16_f32 v209, v218, v219
	v_cvt_pk_bf16_f32 v210, v220, v221
	v_cvt_pk_bf16_f32 v211, v222, v223
	s_mov_b64 s[98:99], 0x58000
	v_lshl_add_u64 v[224:225], v[154:155], 0, s[98:99]
	global_store_dwordx4 v[224:225], v[208:211], off
	v_pk_mul_f32 v[172:173], v[72:73], v[76:77]
	v_pk_mul_f32 v[174:175], v[74:75], v[78:79]
	v_pk_mul_f32 v[176:177], v[64:65], v[68:69]
	v_pk_mul_f32 v[178:179], v[66:67], v[70:71]
	v_pk_add_f32 v[164:165], v[164:165], v[158:159]
	v_pk_add_f32 v[166:167], v[166:167], v[158:159]
	v_pk_add_f32 v[168:169], v[168:169], v[158:159]
	v_pk_add_f32 v[170:171], v[170:171], v[158:159]
	v_rcp_f32_e32 v164, v164
	v_mul_f32_e32 v184, v236, v236
	v_rcp_f32_e32 v165, v165
	v_pk_mul_f32 v[186:187], v[56:57], v[182:183] op_sel_hi:[1,0]
	v_rcp_f32_e32 v166, v166
	v_pk_mul_f32 v[188:189], v[58:59], v[182:183] op_sel_hi:[1,0]
	v_rcp_f32_e32 v167, v167
	v_pk_mul_f32 v[190:191], v[48:49], v[182:183] op_sel_hi:[1,0]
	v_rcp_f32_e32 v168, v168
	v_pk_mul_f32 v[192:193], v[50:51], v[182:183] op_sel_hi:[1,0]
	v_rcp_f32_e32 v169, v169
	v_mul_f32_e32 v204, 0xbfb8aa3b, v237
	v_rcp_f32_e32 v170, v170
	v_mul_f32_e32 v206, v237, v237
	v_rcp_f32_e32 v171, v171
	v_pk_mul_f32 v[164:165], v[164:165], v[162:163] op_sel_hi:[1,0]
	v_exp_f32_e32 v186, v186
	v_pk_mul_f32 v[166:167], v[166:167], v[162:163] op_sel_hi:[1,0]
	v_exp_f32_e32 v187, v187
	v_pk_mul_f32 v[168:169], v[168:169], v[162:163] op_sel_hi:[1,0]
	v_exp_f32_e32 v188, v188
	v_pk_mul_f32 v[170:171], v[170:171], v[162:163] op_sel_hi:[1,0]
	v_exp_f32_e32 v189, v189
	v_pk_mul_f32 v[172:173], v[172:173], v[164:165]
	v_exp_f32_e32 v190, v190
	v_pk_mul_f32 v[174:175], v[174:175], v[166:167]
	v_exp_f32_e32 v191, v191
	v_pk_mul_f32 v[176:177], v[176:177], v[168:169]
	v_exp_f32_e32 v192, v192
	v_pk_mul_f32 v[178:179], v[178:179], v[170:171]
	v_exp_f32_e32 v193, v193
	v_cvt_pk_bf16_f32 v164, v172, v173
	v_cvt_pk_bf16_f32 v165, v174, v175
	v_cvt_pk_bf16_f32 v166, v176, v177
	v_cvt_pk_bf16_f32 v167, v178, v179
	s_mov_b64 s[98:99], 0x84000
	v_lshl_add_u64 v[180:181], v[154:155], 0, s[98:99]
	global_store_dwordx4 v[180:181], v[164:167], off
	v_pk_mul_f32 v[194:195], v[56:57], v[60:61]
	v_pk_mul_f32 v[196:197], v[58:59], v[62:63]
	v_pk_mul_f32 v[198:199], v[48:49], v[52:53]
	v_pk_mul_f32 v[200:201], v[50:51], v[54:55]
	v_pk_add_f32 v[186:187], v[186:187], v[158:159]
	v_pk_add_f32 v[188:189], v[188:189], v[158:159]
	v_pk_add_f32 v[190:191], v[190:191], v[158:159]
	v_pk_add_f32 v[192:193], v[192:193], v[158:159]
	v_rcp_f32_e32 v186, v186
	v_pk_mul_f32 v[208:209], v[40:41], v[204:205] op_sel_hi:[1,0]
	v_rcp_f32_e32 v187, v187
	v_pk_mul_f32 v[210:211], v[42:43], v[204:205] op_sel_hi:[1,0]
	v_rcp_f32_e32 v188, v188
	v_pk_mul_f32 v[212:213], v[32:33], v[204:205] op_sel_hi:[1,0]
	v_rcp_f32_e32 v189, v189
	v_pk_mul_f32 v[214:215], v[34:35], v[204:205] op_sel_hi:[1,0]
	v_rcp_f32_e32 v190, v190
	v_mul_f32_e32 v160, 0xbfb8aa3b, v238
	v_rcp_f32_e32 v191, v191
	v_mul_f32_e32 v162, v238, v238
	v_rcp_f32_e32 v192, v192
	v_pk_mul_f32 v[164:165], v[24:25], v[160:161] op_sel_hi:[1,0]
	v_rcp_f32_e32 v193, v193
	v_pk_mul_f32 v[186:187], v[186:187], v[184:185] op_sel_hi:[1,0]
	v_exp_f32_e32 v208, v208
	v_pk_mul_f32 v[188:189], v[188:189], v[184:185] op_sel_hi:[1,0]
	v_exp_f32_e32 v209, v209
	v_pk_mul_f32 v[190:191], v[190:191], v[184:185] op_sel_hi:[1,0]
	v_exp_f32_e32 v210, v210
	v_pk_mul_f32 v[192:193], v[192:193], v[184:185] op_sel_hi:[1,0]
	v_exp_f32_e32 v211, v211
	v_pk_mul_f32 v[194:195], v[194:195], v[186:187]
	v_exp_f32_e32 v212, v212
	v_pk_mul_f32 v[196:197], v[196:197], v[188:189]
	v_exp_f32_e32 v213, v213
	v_pk_mul_f32 v[198:199], v[198:199], v[190:191]
	v_exp_f32_e32 v214, v214
	v_pk_mul_f32 v[200:201], v[200:201], v[192:193]
	v_exp_f32_e32 v215, v215
	v_cvt_pk_bf16_f32 v186, v194, v195
	v_cvt_pk_bf16_f32 v187, v196, v197
	v_cvt_pk_bf16_f32 v188, v198, v199
	v_cvt_pk_bf16_f32 v189, v200, v201
	s_mov_b64 s[98:99], 0x160000
	v_lshl_add_u64 v[202:203], v[154:155], 0, s[98:99]
	global_store_dwordx4 v[202:203], v[186:189], off
	v_pk_mul_f32 v[216:217], v[40:41], v[44:45]
	v_pk_mul_f32 v[218:219], v[42:43], v[46:47]
	v_pk_mul_f32 v[220:221], v[32:33], v[36:37]
	v_pk_mul_f32 v[222:223], v[34:35], v[38:39]
	v_pk_add_f32 v[208:209], v[208:209], v[158:159]
	v_pk_add_f32 v[210:211], v[210:211], v[158:159]
	v_pk_add_f32 v[212:213], v[212:213], v[158:159]
	v_pk_add_f32 v[214:215], v[214:215], v[158:159]
	v_rcp_f32_e32 v208, v208
	v_pk_mul_f32 v[166:167], v[26:27], v[160:161] op_sel_hi:[1,0]
	v_rcp_f32_e32 v209, v209
	v_pk_mul_f32 v[168:169], v[16:17], v[160:161] op_sel_hi:[1,0]
	v_rcp_f32_e32 v210, v210
	v_pk_mul_f32 v[170:171], v[18:19], v[160:161] op_sel_hi:[1,0]
	v_rcp_f32_e32 v211, v211
	v_mul_f32_e32 v182, 0xbfb8aa3b, v239
	v_rcp_f32_e32 v212, v212
	v_mul_f32_e32 v184, v239, v239
	v_rcp_f32_e32 v213, v213
	v_pk_mul_f32 v[186:187], v[8:9], v[182:183] op_sel_hi:[1,0]
	v_rcp_f32_e32 v214, v214
	v_pk_mul_f32 v[188:189], v[10:11], v[182:183] op_sel_hi:[1,0]
	v_rcp_f32_e32 v215, v215
	v_pk_mul_f32 v[208:209], v[208:209], v[206:207] op_sel_hi:[1,0]
	v_exp_f32_e32 v164, v164
	v_pk_mul_f32 v[210:211], v[210:211], v[206:207] op_sel_hi:[1,0]
	v_exp_f32_e32 v165, v165
	v_pk_mul_f32 v[212:213], v[212:213], v[206:207] op_sel_hi:[1,0]
	v_exp_f32_e32 v166, v166
	v_pk_mul_f32 v[214:215], v[214:215], v[206:207] op_sel_hi:[1,0]
	v_exp_f32_e32 v167, v167
	v_pk_mul_f32 v[216:217], v[216:217], v[208:209]
	v_exp_f32_e32 v168, v168
	v_pk_mul_f32 v[218:219], v[218:219], v[210:211]
	v_exp_f32_e32 v169, v169
	v_pk_mul_f32 v[220:221], v[220:221], v[212:213]
	v_exp_f32_e32 v170, v170
	v_pk_mul_f32 v[222:223], v[222:223], v[214:215]
	v_exp_f32_e32 v171, v171
	v_cvt_pk_bf16_f32 v208, v216, v217
	v_cvt_pk_bf16_f32 v209, v218, v219
	v_cvt_pk_bf16_f32 v210, v220, v221
	v_cvt_pk_bf16_f32 v211, v222, v223
	s_mov_b64 s[98:99], 0x18c000
	v_lshl_add_u64 v[224:225], v[154:155], 0, s[98:99]
	global_store_dwordx4 v[224:225], v[208:211], off
	v_pk_mul_f32 v[172:173], v[24:25], v[28:29]
	v_pk_mul_f32 v[174:175], v[26:27], v[30:31]
	v_pk_mul_f32 v[176:177], v[16:17], v[20:21]
	v_pk_mul_f32 v[178:179], v[18:19], v[22:23]
	v_pk_add_f32 v[164:165], v[164:165], v[158:159]
	v_pk_add_f32 v[166:167], v[166:167], v[158:159]
	v_pk_add_f32 v[168:169], v[168:169], v[158:159]
	v_pk_add_f32 v[170:171], v[170:171], v[158:159]
	v_rcp_f32_e32 v164, v164
	v_pk_mul_f32 v[190:191], v[4:5], v[182:183] op_sel_hi:[1,0]
	v_rcp_f32_e32 v165, v165
	v_pk_mul_f32 v[192:193], v[6:7], v[182:183] op_sel_hi:[1,0]
	v_rcp_f32_e32 v166, v166
	v_rcp_f32_e32 v167, v167
	v_rcp_f32_e32 v168, v168
	v_rcp_f32_e32 v169, v169
	v_rcp_f32_e32 v170, v170
	v_rcp_f32_e32 v171, v171
	v_pk_mul_f32 v[164:165], v[164:165], v[162:163] op_sel_hi:[1,0]
	v_exp_f32_e32 v186, v186
	v_pk_mul_f32 v[166:167], v[166:167], v[162:163] op_sel_hi:[1,0]
	v_exp_f32_e32 v187, v187
	v_pk_mul_f32 v[168:169], v[168:169], v[162:163] op_sel_hi:[1,0]
	v_exp_f32_e32 v188, v188
	v_pk_mul_f32 v[170:171], v[170:171], v[162:163] op_sel_hi:[1,0]
	v_exp_f32_e32 v189, v189
	v_pk_mul_f32 v[172:173], v[172:173], v[164:165]
	v_exp_f32_e32 v190, v190
	v_pk_mul_f32 v[174:175], v[174:175], v[166:167]
	v_exp_f32_e32 v191, v191
	v_pk_mul_f32 v[176:177], v[176:177], v[168:169]
	v_exp_f32_e32 v192, v192
	v_pk_mul_f32 v[178:179], v[178:179], v[170:171]
	v_exp_f32_e32 v193, v193
	v_cvt_pk_bf16_f32 v164, v172, v173
	v_cvt_pk_bf16_f32 v165, v174, v175
	v_cvt_pk_bf16_f32 v166, v176, v177
	v_cvt_pk_bf16_f32 v167, v178, v179
	s_mov_b64 s[98:99], 0x1b8000
	v_lshl_add_u64 v[180:181], v[154:155], 0, s[98:99]
	global_store_dwordx4 v[180:181], v[164:167], off
	v_pk_mul_f32 v[194:195], v[8:9], v[12:13]
	v_pk_mul_f32 v[196:197], v[10:11], v[14:15]
	v_pk_mul_f32 v[198:199], v[4:5], v[0:1]
	v_pk_mul_f32 v[200:201], v[6:7], v[2:3]
	v_pk_add_f32 v[186:187], v[186:187], v[158:159]
	v_pk_add_f32 v[188:189], v[188:189], v[158:159]
	v_pk_add_f32 v[190:191], v[190:191], v[158:159]
	v_pk_add_f32 v[192:193], v[192:193], v[158:159]
	v_rcp_f32_e32 v186, v186
	v_rcp_f32_e32 v187, v187
	v_rcp_f32_e32 v188, v188
	v_rcp_f32_e32 v189, v189
	v_rcp_f32_e32 v190, v190
	v_rcp_f32_e32 v191, v191
	v_rcp_f32_e32 v192, v192
	v_rcp_f32_e32 v193, v193
	v_pk_mul_f32 v[186:187], v[186:187], v[184:185] op_sel_hi:[1,0]
	v_pk_mul_f32 v[188:189], v[188:189], v[184:185] op_sel_hi:[1,0]
	v_pk_mul_f32 v[190:191], v[190:191], v[184:185] op_sel_hi:[1,0]
	v_pk_mul_f32 v[192:193], v[192:193], v[184:185] op_sel_hi:[1,0]
	v_pk_mul_f32 v[194:195], v[194:195], v[186:187]
	v_pk_mul_f32 v[196:197], v[196:197], v[188:189]
	v_pk_mul_f32 v[198:199], v[198:199], v[190:191]
	v_pk_mul_f32 v[200:201], v[200:201], v[192:193]
	v_cvt_pk_bf16_f32 v186, v194, v195
	v_cvt_pk_bf16_f32 v187, v196, v197
	v_cvt_pk_bf16_f32 v188, v198, v199
	v_cvt_pk_bf16_f32 v189, v200, v201
	s_mov_b64 s[98:99], 0x1e4000
	v_lshl_add_u64 v[202:203], v[154:155], 0, s[98:99]
	global_store_dwordx4 v[202:203], v[186:189], off
	s_and_b64 vcc, exec, s[2:3]
	s_mov_b64 s[2:3], -1
	s_cbranch_vccnz .LBB0_1486
	s_andn2_b64 vcc, exec, s[16:17]
	s_cbranch_vccnz .LBB0_1485
	s_barrier
	s_branch .LBB0_1485
